# wait-skip with s101 flag (same logic as v38)
# speedup vs baseline: 1.0014x; 1.0014x over previous
; #define STAGE(bufoff, GB) do { const char* g_ = (GB); \
;         _Pragma("unroll") for (int i_ = 0; i_ < 2; ++i_) __builtin_amdgcn_global_load_lds((const unsigned*)(g_ + voff[i_]), (LAS3 unsigned*)(L + (bufoff) + stoff + i_ * 8192), 16, 0, 0); } while (0)
; #define LDA(dst, b, h) do { _Pragma("unroll") for (int m = 0; m < 4; ++m) _Pragma("unroll") for (int k = 0; k < 2; ++k) dst[m][k] = *(const LAS3 bf16x8*)(L + SA(b, h) + aoff + m * 2048 + k * 1024); } while (0)
; #define LDB(dst, b, h) do { _Pragma("unroll") for (int n = 0; n < 2; ++n) _Pragma("unroll") for (int k = 0; k < 2; ++k) dst[n][k] = *(const LAS3 bf16x8*)(L + SB(b, h) + boff + n * 2048 + k * 1024); } while (0)
; #define WAIT_V(n) asm volatile("s_waitcnt vmcnt(" #n ")" ::: "memory")
; #define WAIT_L(n) asm volatile("s_waitcnt lgkmcnt(" #n ")" ::: "memory")
; #define BAR __builtin_amdgcn_s_barrier()
; #define SCHED __builtin_amdgcn_sched_barrier(0)
; template <int EPI>
; DI void gemm_phase(const bf16_t* __restrict__ A, const bf16_t* __restrict__ Bt, const int K, const int N, const Params& p, const int layer_j, char* lds) {
;     ...
;         for (int t = 0; t < nt; t += 2) {
;             const bool last = (t == nt - 2);
;             const char* a1 = cA + (size_t)(t + 1) * kstep;
;             const char* a2 = last ? nA : cA + (size_t)(t + 2) * kstep; const char* b2 = last ? nB : cB + (size_t)(t + 2) * kstep;
;             const char* a3 = a2 + kstep; const char* b3 = b2 + kstep;
;             LDB(B0, 0, 0); LDB(B1, 0, 1); SCHED; LDA(At, 0, 0); STAGE(SA(1, 1), a1 + hstep);
;             WAIT_V(8); WAIT_L(0); BAR; MMA(0, 0, At, B0); MMA(0, 1, At, B1); BAR; SCHED;
;             LDA(At, 0, 1); STAGE(SB(0, 0), b2); STAGE(SB(0, 1), b2 + hstep); STAGE(SA(0, 0), a2);
;             WAIT_V(8); WAIT_L(0); BAR; MMA(1, 0, At, B0); MMA(1, 1, At, B1); BAR; SCHED;
.LBB0_43:
	s_cmp_eq_u32 s87, 1
	s_cselect_b32 s101, 1, s28
	v_add_u32_e32 v164, 0x10000, v138
	v_add_u32_e32 v180, 0x14000, v138
	s_add_u32 s6, s38, s28
	ds_read_b128 v[152:155], v164
	ds_read_b128 v[156:159], v164 offset:1024
	ds_read_b128 v[160:163], v164 offset:2048
	ds_read_b128 v[164:167], v164 offset:3072
	ds_read_b128 v[168:171], v180
	ds_read_b128 v[172:175], v180 offset:1024
	ds_read_b128 v[176:179], v180 offset:2048
	ds_read_b128 v[180:183], v180 offset:3072
	s_addc_u32 s7, s39, s29
	s_add_u32 s6, s6, 0x6681100
	s_addc_u32 s7, s7, 0
	s_add_u32 s30, vcc_lo, s28
	s_addc_u32 s31, vcc_hi, s29
	s_cmpk_eq_i32 s28, 0x700
	s_cselect_b32 s35, s17, s7
	s_cselect_b32 s34, s13, s6
	s_cselect_b32 s31, s88, s31
	s_cselect_b32 s30, s25, s30
	v_add_u32_e32 v194, 0xc000, v136
	v_lshl_add_u64 v[192:193], v[134:135], 0, s[28:29]
	v_readfirstlane_b32 s6, v194
	v_add_u32_e32 v194, 0xe000, v136
	s_mov_b32 m0, s6
	v_readfirstlane_b32 s6, v194
	ds_read_b128 v[184:187], v137
	ds_read_b128 v[188:191], v137 offset:1024
	ds_read_b128 v[204:207], v137 offset:2048
	ds_read_b128 v[208:211], v137 offset:3072
	ds_read_b128 v[212:215], v137 offset:4096
	ds_read_b128 v[216:219], v137 offset:5120
	ds_read_b128 v[220:223], v137 offset:6144
	ds_read_b128 v[224:227], v137 offset:7168
	global_load_lds_dwordx4 v[192:193], off
	v_lshl_add_u64 v[192:193], v[132:133], 0, s[28:29]
	s_mov_b32 m0, s6
	s_nop 0
	global_load_lds_dwordx4 v[192:193], off
	s_cmp_eq_u32 s101, 0
	s_cbranch_scc1 .Lskipw_ffn_0
	s_waitcnt vmcnt(8)
.Lskipw_ffn_0:
	s_waitcnt lgkmcnt(0)
	s_barrier
	s_setprio 1
	s_waitcnt lgkmcnt(0)
	v_mfma_f32_16x16x32_bf16 v[126:129], v[152:155], v[184:187], v[126:129]
	v_mfma_f32_16x16x32_bf16 v[118:121], v[160:163], v[184:187], v[118:121]
	v_mfma_f32_16x16x32_bf16 v[110:113], v[152:155], v[204:207], v[110:113]
	v_mfma_f32_16x16x32_bf16 v[102:105], v[160:163], v[204:207], v[102:105]
	v_mfma_f32_16x16x32_bf16 v[94:97], v[152:155], v[212:215], v[94:97]
	v_mfma_f32_16x16x32_bf16 v[86:89], v[160:163], v[212:215], v[86:89]
	v_mfma_f32_16x16x32_bf16 v[78:81], v[152:155], v[220:223], v[78:81]
	v_mfma_f32_16x16x32_bf16 v[70:73], v[160:163], v[220:223], v[70:73]
	v_mfma_f32_16x16x32_bf16 v[126:129], v[156:159], v[188:191], v[126:129]
	v_mfma_f32_16x16x32_bf16 v[118:121], v[164:167], v[188:191], v[118:121]
	v_mfma_f32_16x16x32_bf16 v[110:113], v[156:159], v[208:211], v[110:113]
	v_mfma_f32_16x16x32_bf16 v[102:105], v[164:167], v[208:211], v[102:105]
	v_mfma_f32_16x16x32_bf16 v[94:97], v[156:159], v[216:219], v[94:97]
	v_mfma_f32_16x16x32_bf16 v[86:89], v[164:167], v[216:219], v[86:89]
	v_mfma_f32_16x16x32_bf16 v[78:81], v[156:159], v[224:227], v[78:81]
	v_mfma_f32_16x16x32_bf16 v[70:73], v[164:167], v[224:227], v[70:73]
	s_setprio 0
	s_setprio 1
	v_mfma_f32_16x16x32_bf16 v[122:125], v[168:171], v[184:187], v[122:125]
	v_mfma_f32_16x16x32_bf16 v[114:117], v[176:179], v[184:187], v[114:117]
	v_mfma_f32_16x16x32_bf16 v[106:109], v[168:171], v[204:207], v[106:109]
	v_mfma_f32_16x16x32_bf16 v[98:101], v[176:179], v[204:207], v[98:101]
	v_mfma_f32_16x16x32_bf16 v[90:93], v[168:171], v[212:215], v[90:93]
	v_mfma_f32_16x16x32_bf16 v[82:85], v[176:179], v[212:215], v[82:85]
	v_mfma_f32_16x16x32_bf16 v[74:77], v[168:171], v[220:223], v[74:77]
	v_mfma_f32_16x16x32_bf16 v[66:69], v[176:179], v[220:223], v[66:69]
	v_mfma_f32_16x16x32_bf16 v[122:125], v[172:175], v[188:191], v[122:125]
	v_mfma_f32_16x16x32_bf16 v[114:117], v[180:183], v[188:191], v[114:117]
	v_mfma_f32_16x16x32_bf16 v[106:109], v[172:175], v[208:211], v[106:109]
	v_mfma_f32_16x16x32_bf16 v[98:101], v[180:183], v[208:211], v[98:101]
	v_mfma_f32_16x16x32_bf16 v[90:93], v[172:175], v[216:219], v[90:93]
	v_mfma_f32_16x16x32_bf16 v[82:85], v[180:183], v[216:219], v[82:85]
	v_mfma_f32_16x16x32_bf16 v[74:77], v[172:175], v[224:227], v[74:77]
	v_mfma_f32_16x16x32_bf16 v[66:69], v[180:183], v[224:227], v[66:69]
	s_setprio 0
	s_barrier
	v_readfirstlane_b32 s6, v139
	v_lshl_add_u64 v[192:193], s[30:31], 0, v[32:33]
	s_mov_b32 m0, s6
	v_readfirstlane_b32 s6, v140
	ds_read_b128 v[184:187], v137 offset:16384
	ds_read_b128 v[188:191], v137 offset:17408
	ds_read_b128 v[204:207], v137 offset:18432
	ds_read_b128 v[208:211], v137 offset:19456
	ds_read_b128 v[212:215], v137 offset:20480
	ds_read_b128 v[216:219], v137 offset:21504
	ds_read_b128 v[220:223], v137 offset:22528
	ds_read_b128 v[224:227], v137 offset:23552
	global_load_lds_dwordx4 v[192:193], off
	s_mov_b32 m0, s6
	s_add_u32 s6, s30, 0x40000
	v_lshl_add_u64 v[194:195], s[30:31], 0, v[130:131]
	s_addc_u32 s7, s31, 0
	v_readfirstlane_b32 s10, v141
	global_load_lds_dwordx4 v[194:195], off
	v_lshl_add_u64 v[228:229], s[6:7], 0, v[32:33]
	s_mov_b32 m0, s10
	v_lshl_add_u64 v[230:231], s[34:35], 0, v[130:131]
	global_load_lds_dwordx4 v[228:229], off
	v_lshl_add_u64 v[228:229], s[6:7], 0, v[130:131]
	v_readfirstlane_b32 s6, v142
	s_mov_b32 m0, s6
	v_readfirstlane_b32 s6, v136
	global_load_lds_dwordx4 v[228:229], off
	v_lshl_add_u64 v[228:229], s[34:35], 0, v[32:33]
	s_mov_b32 m0, s6
	v_readfirstlane_b32 s6, v143
	global_load_lds_dwordx4 v[228:229], off
	s_mov_b32 m0, s6
	s_nop 0
	global_load_lds_dwordx4 v[230:231], off
	s_cmp_eq_u32 s101, 0
	s_cbranch_scc1 .Lskipw_ffn_1
	s_waitcnt vmcnt(8)

; #define STAGE(bufoff, GB) do { const char* g_ = (GB); \
;         _Pragma("unroll") for (int i_ = 0; i_ < 2; ++i_) __builtin_amdgcn_global_load_lds((const unsigned*)(g_ + voff[i_]), (LAS3 unsigned*)(L + (bufoff) + stoff + i_ * 8192), 16, 0, 0); } while (0)
; #define LDA(dst, b, h) do { _Pragma("unroll") for (int m = 0; m < 4; ++m) _Pragma("unroll") for (int k = 0; k < 2; ++k) dst[m][k] = *(const LAS3 bf16x8*)(L + SA(b, h) + aoff + m * 2048 + k * 1024); } while (0)
; #define LDB(dst, b, h) do { _Pragma("unroll") for (int n = 0; n < 2; ++n) _Pragma("unroll") for (int k = 0; k < 2; ++k) dst[n][k] = *(const LAS3 bf16x8*)(L + SB(b, h) + boff + n * 2048 + k * 1024); } while (0)
; #define WAIT_V(n) asm volatile("s_waitcnt vmcnt(" #n ")" ::: "memory")
; #define WAIT_L(n) asm volatile("s_waitcnt lgkmcnt(" #n ")" ::: "memory")
; #define BAR __builtin_amdgcn_s_barrier()
; #define SCHED __builtin_amdgcn_sched_barrier(0)
; template <int EPI>
; DI void gemm_phase(const bf16_t* __restrict__ A, const bf16_t* __restrict__ Bt, const int K, const int N, const Params& p, const int layer_j, char* lds) {
;     ...
;         for (int t = 0; t < nt; t += 2) {
;             const bool last = (t == nt - 2);
;             const char* a1 = cA + (size_t)(t + 1) * kstep;
;             const char* a2 = last ? nA : cA + (size_t)(t + 2) * kstep; const char* b2 = last ? nB : cB + (size_t)(t + 2) * kstep;
;             const char* a3 = a2 + kstep; const char* b3 = b2 + kstep;
;             LDB(B0, 0, 0); LDB(B1, 0, 1); SCHED; LDA(At, 0, 0); STAGE(SA(1, 1), a1 + hstep);
;             WAIT_V(8); WAIT_L(0); BAR; MMA(0, 0, At, B0); MMA(0, 1, At, B1); BAR; SCHED;
;             LDA(At, 0, 1); STAGE(SB(0, 0), b2); STAGE(SB(0, 1), b2 + hstep); STAGE(SA(0, 0), a2);
;             WAIT_V(8); WAIT_L(0); BAR; MMA(1, 0, At, B0); MMA(1, 1, At, B1); BAR; SCHED;
.LBB0_338:
	s_cmp_eq_u32 s66, 1
	s_cselect_b32 s101, 1, s28
	v_add_u32_e32 v148, 0x10000, v186
	v_add_u32_e32 v164, 0x14000, v186
	s_add_u32 s16, s87, s28
	ds_read_b128 v[136:139], v148
	ds_read_b128 v[140:143], v148 offset:1024
	ds_read_b128 v[144:147], v148 offset:2048
	ds_read_b128 v[148:151], v148 offset:3072
	ds_read_b128 v[152:155], v164
	ds_read_b128 v[156:159], v164 offset:1024
	ds_read_b128 v[160:163], v164 offset:2048
	ds_read_b128 v[164:167], v164 offset:3072
	s_addc_u32 s17, s88, s29
	s_add_u32 s16, s16, 0x6681100
	s_addc_u32 s17, s17, 0
	s_add_u32 s30, s67, s28
	s_addc_u32 s31, s86, s29
	s_cmpk_eq_i32 s28, 0x700
	s_cselect_b32 s35, s9, s17
	s_cselect_b32 s34, s5, s16
	s_cselect_b32 s31, s23, s31
	s_cselect_b32 s30, s21, s30
	v_add_u32_e32 v192, 0xc000, v184
	v_lshl_add_u64 v[194:195], v[134:135], 0, s[28:29]
	v_readfirstlane_b32 s16, v192
	v_add_u32_e32 v192, 0xe000, v184
	s_mov_b32 m0, s16
	v_readfirstlane_b32 s16, v192
	ds_read_b128 v[168:171], v185
	ds_read_b128 v[172:175], v185 offset:1024
	ds_read_b128 v[176:179], v185 offset:2048
	ds_read_b128 v[180:183], v185 offset:3072
	ds_read_b128 v[212:215], v185 offset:4096
	ds_read_b128 v[216:219], v185 offset:5120
	ds_read_b128 v[220:223], v185 offset:6144
	ds_read_b128 v[224:227], v185 offset:7168
	global_load_lds_dwordx4 v[194:195], off
	v_lshl_add_u64 v[194:195], v[132:133], 0, s[28:29]
	s_mov_b32 m0, s16
	s_nop 0
	global_load_lds_dwordx4 v[194:195], off
	s_cmp_eq_u32 s101, 0
	s_cbranch_scc1 .Lskipw_rec_0
	s_waitcnt vmcnt(8)
.Lskipw_rec_0:
	s_waitcnt lgkmcnt(0)
	s_barrier
	s_setprio 1
	s_waitcnt lgkmcnt(0)
	v_mfma_f32_16x16x32_bf16 v[126:129], v[136:139], v[168:171], v[126:129]
	v_mfma_f32_16x16x32_bf16 v[122:125], v[144:147], v[168:171], v[122:125]
	v_mfma_f32_16x16x32_bf16 v[110:113], v[136:139], v[176:179], v[110:113]
	v_mfma_f32_16x16x32_bf16 v[106:109], v[144:147], v[176:179], v[106:109]
	v_mfma_f32_16x16x32_bf16 v[94:97], v[136:139], v[212:215], v[94:97]
	v_mfma_f32_16x16x32_bf16 v[90:93], v[144:147], v[212:215], v[90:93]
	v_mfma_f32_16x16x32_bf16 v[78:81], v[136:139], v[220:223], v[78:81]
	v_mfma_f32_16x16x32_bf16 v[74:77], v[144:147], v[220:223], v[74:77]
	v_mfma_f32_16x16x32_bf16 v[126:129], v[140:143], v[172:175], v[126:129]
	v_mfma_f32_16x16x32_bf16 v[122:125], v[148:151], v[172:175], v[122:125]
	v_mfma_f32_16x16x32_bf16 v[110:113], v[140:143], v[180:183], v[110:113]
	v_mfma_f32_16x16x32_bf16 v[106:109], v[148:151], v[180:183], v[106:109]
	v_mfma_f32_16x16x32_bf16 v[94:97], v[140:143], v[216:219], v[94:97]
	v_mfma_f32_16x16x32_bf16 v[90:93], v[148:151], v[216:219], v[90:93]
	v_mfma_f32_16x16x32_bf16 v[78:81], v[140:143], v[224:227], v[78:81]
	v_mfma_f32_16x16x32_bf16 v[74:77], v[148:151], v[224:227], v[74:77]
	s_setprio 0
	s_setprio 1
	v_mfma_f32_16x16x32_bf16 v[118:121], v[152:155], v[168:171], v[118:121]
	v_mfma_f32_16x16x32_bf16 v[114:117], v[160:163], v[168:171], v[114:117]
	v_mfma_f32_16x16x32_bf16 v[102:105], v[152:155], v[176:179], v[102:105]
	v_mfma_f32_16x16x32_bf16 v[98:101], v[160:163], v[176:179], v[98:101]
	v_mfma_f32_16x16x32_bf16 v[86:89], v[152:155], v[212:215], v[86:89]
	v_mfma_f32_16x16x32_bf16 v[82:85], v[160:163], v[212:215], v[82:85]
	v_mfma_f32_16x16x32_bf16 v[38:41], v[152:155], v[220:223], v[38:41]
	v_mfma_f32_16x16x32_bf16 v[16:19], v[160:163], v[220:223], v[16:19]
	v_mfma_f32_16x16x32_bf16 v[118:121], v[156:159], v[172:175], v[118:121]
	v_mfma_f32_16x16x32_bf16 v[114:117], v[164:167], v[172:175], v[114:117]
	v_mfma_f32_16x16x32_bf16 v[102:105], v[156:159], v[180:183], v[102:105]
	v_mfma_f32_16x16x32_bf16 v[98:101], v[164:167], v[180:183], v[98:101]
	v_mfma_f32_16x16x32_bf16 v[86:89], v[156:159], v[216:219], v[86:89]
	v_mfma_f32_16x16x32_bf16 v[82:85], v[164:167], v[216:219], v[82:85]
	v_mfma_f32_16x16x32_bf16 v[38:41], v[156:159], v[224:227], v[38:41]
	v_mfma_f32_16x16x32_bf16 v[16:19], v[164:167], v[224:227], v[16:19]
	s_setprio 0
	s_barrier
	v_readfirstlane_b32 s16, v187
	v_lshl_add_u64 v[194:195], s[30:31], 0, v[32:33]
	s_mov_b32 m0, s16
	v_readfirstlane_b32 s16, v188
	ds_read_b128 v[168:171], v185 offset:16384
	ds_read_b128 v[172:175], v185 offset:17408
	ds_read_b128 v[176:179], v185 offset:18432
	ds_read_b128 v[180:183], v185 offset:19456
	ds_read_b128 v[212:215], v185 offset:20480
	ds_read_b128 v[216:219], v185 offset:21504
	ds_read_b128 v[220:223], v185 offset:22528
	ds_read_b128 v[224:227], v185 offset:23552
	global_load_lds_dwordx4 v[194:195], off
	s_mov_b32 m0, s16
	s_add_u32 s16, s30, 0x40000
	v_lshl_add_u64 v[228:229], s[30:31], 0, v[130:131]
	s_addc_u32 s17, s31, 0
	v_readfirstlane_b32 s6, v189
	global_load_lds_dwordx4 v[228:229], off
	v_lshl_add_u64 v[230:231], s[16:17], 0, v[32:33]
	s_mov_b32 m0, s6
	v_readfirstlane_b32 s6, v190
	global_load_lds_dwordx4 v[230:231], off
	v_lshl_add_u64 v[230:231], s[16:17], 0, v[130:131]
	s_mov_b32 m0, s6
	v_readfirstlane_b32 s6, v184
	global_load_lds_dwordx4 v[230:231], off
	v_lshl_add_u64 v[230:231], s[34:35], 0, v[32:33]
	s_mov_b32 m0, s6
	v_readfirstlane_b32 s6, v191
	global_load_lds_dwordx4 v[230:231], off
	v_lshl_add_u64 v[232:233], s[34:35], 0, v[130:131]
	s_mov_b32 m0, s6
	s_nop 0
	global_load_lds_dwordx4 v[232:233], off
	s_cmp_eq_u32 s101, 0
	s_cbranch_scc1 .Lskipw_rec_1
	s_waitcnt vmcnt(8)

; #define STAGE(bufoff, GB) do { const char* g_ = (GB); \
;         _Pragma("unroll") for (int i_ = 0; i_ < 2; ++i_) __builtin_amdgcn_global_load_lds((const unsigned*)(g_ + voff[i_]), (LAS3 unsigned*)(L + (bufoff) + stoff + i_ * 8192), 16, 0, 0); } while (0)
; #define LDA(dst, b, h) do { _Pragma("unroll") for (int m = 0; m < 4; ++m) _Pragma("unroll") for (int k = 0; k < 2; ++k) dst[m][k] = *(const LAS3 bf16x8*)(L + SA(b, h) + aoff + m * 2048 + k * 1024); } while (0)
; #define LDB(dst, b, h) do { _Pragma("unroll") for (int n = 0; n < 2; ++n) _Pragma("unroll") for (int k = 0; k < 2; ++k) dst[n][k] = *(const LAS3 bf16x8*)(L + SB(b, h) + boff + n * 2048 + k * 1024); } while (0)
; #define WAIT_V(n) asm volatile("s_waitcnt vmcnt(" #n ")" ::: "memory")
; #define WAIT_L(n) asm volatile("s_waitcnt lgkmcnt(" #n ")" ::: "memory")
; #define BAR __builtin_amdgcn_s_barrier()
; #define SCHED __builtin_amdgcn_sched_barrier(0)
; template <int EPI>
; DI void gemm_phase(const bf16_t* __restrict__ A, const bf16_t* __restrict__ Bt, const int K, const int N, const Params& p, const int layer_j, char* lds) {
;     ...
;             WAIT_V(8); WAIT_L(0); BAR; MMA(0, 0, At, B0); MMA(0, 1, At, B1); BAR; SCHED;
;             LDA(At, 0, 1); STAGE(SB(0, 0), b2); STAGE(SB(0, 1), b2 + hstep); STAGE(SA(0, 0), a2);
;             WAIT_V(8); WAIT_L(0); BAR; MMA(1, 0, At, B0); MMA(1, 1, At, B1); BAR; SCHED;
;             LDB(B0, 1, 0); LDB(B1, 1, 1); SCHED; LDA(At, 1, 0); STAGE(SA(0, 1), a2 + hstep);
;             WAIT_V(8); WAIT_L(0); BAR; MMA(0, 0, At, B0); MMA(0, 1, At, B1); BAR; SCHED;
;             LDA(At, 1, 1); STAGE(SB(1, 0), b3); STAGE(SB(1, 1), b3 + hstep); STAGE(SA(1, 0), a3);
.Lskipw_recns_0:
	s_waitcnt lgkmcnt(0)
	s_barrier
	s_setprio 1
	s_waitcnt lgkmcnt(0)
	v_mfma_f32_16x16x32_bf16 v[126:129], v[168:171], v[136:139], v[126:129]
	v_mfma_f32_16x16x32_bf16 v[122:125], v[168:171], v[144:147], v[122:125]
	v_mfma_f32_16x16x32_bf16 v[110:113], v[176:179], v[136:139], v[110:113]
	v_mfma_f32_16x16x32_bf16 v[106:109], v[176:179], v[144:147], v[106:109]
	v_mfma_f32_16x16x32_bf16 v[94:97], v[212:215], v[136:139], v[94:97]
	v_mfma_f32_16x16x32_bf16 v[90:93], v[212:215], v[144:147], v[90:93]
	v_mfma_f32_16x16x32_bf16 v[78:81], v[220:223], v[136:139], v[78:81]
	v_mfma_f32_16x16x32_bf16 v[74:77], v[220:223], v[144:147], v[74:77]
	v_mfma_f32_16x16x32_bf16 v[126:129], v[172:175], v[140:143], v[126:129]
	v_mfma_f32_16x16x32_bf16 v[122:125], v[172:175], v[148:151], v[122:125]
	v_mfma_f32_16x16x32_bf16 v[110:113], v[180:183], v[140:143], v[110:113]
	v_mfma_f32_16x16x32_bf16 v[106:109], v[180:183], v[148:151], v[106:109]
	v_mfma_f32_16x16x32_bf16 v[94:97], v[216:219], v[140:143], v[94:97]
	v_mfma_f32_16x16x32_bf16 v[90:93], v[216:219], v[148:151], v[90:93]
	v_mfma_f32_16x16x32_bf16 v[78:81], v[224:227], v[140:143], v[78:81]
	v_mfma_f32_16x16x32_bf16 v[74:77], v[224:227], v[148:151], v[74:77]
	s_setprio 0
	s_setprio 1
	v_mfma_f32_16x16x32_bf16 v[118:121], v[168:171], v[152:155], v[118:121]
	v_mfma_f32_16x16x32_bf16 v[114:117], v[168:171], v[160:163], v[114:117]
	v_mfma_f32_16x16x32_bf16 v[102:105], v[176:179], v[152:155], v[102:105]
	v_mfma_f32_16x16x32_bf16 v[98:101], v[176:179], v[160:163], v[98:101]
	v_mfma_f32_16x16x32_bf16 v[86:89], v[212:215], v[152:155], v[86:89]
	v_mfma_f32_16x16x32_bf16 v[82:85], v[212:215], v[160:163], v[82:85]
	v_mfma_f32_16x16x32_bf16 v[38:41], v[220:223], v[152:155], v[38:41]
	v_mfma_f32_16x16x32_bf16 v[16:19], v[220:223], v[160:163], v[16:19]
	v_mfma_f32_16x16x32_bf16 v[118:121], v[172:175], v[156:159], v[118:121]
	v_mfma_f32_16x16x32_bf16 v[114:117], v[172:175], v[164:167], v[114:117]
	v_mfma_f32_16x16x32_bf16 v[102:105], v[180:183], v[156:159], v[102:105]
	v_mfma_f32_16x16x32_bf16 v[98:101], v[180:183], v[164:167], v[98:101]
	v_mfma_f32_16x16x32_bf16 v[86:89], v[216:219], v[156:159], v[86:89]
	v_mfma_f32_16x16x32_bf16 v[82:85], v[216:219], v[164:167], v[82:85]
	v_mfma_f32_16x16x32_bf16 v[38:41], v[224:227], v[156:159], v[38:41]
	v_mfma_f32_16x16x32_bf16 v[16:19], v[224:227], v[164:167], v[16:19]
	s_setprio 0
	s_barrier
	v_readfirstlane_b32 s16, v187
	v_lshl_add_u64 v[194:195], s[30:31], 0, v[32:33]
	s_mov_b32 m0, s16
	v_readfirstlane_b32 s16, v188
	ds_read_b128 v[168:171], v185 offset:16384
	ds_read_b128 v[172:175], v185 offset:17408
	ds_read_b128 v[176:179], v185 offset:18432
	ds_read_b128 v[180:183], v185 offset:19456
	ds_read_b128 v[212:215], v185 offset:20480
	ds_read_b128 v[216:219], v185 offset:21504
	ds_read_b128 v[220:223], v185 offset:22528
	ds_read_b128 v[224:227], v185 offset:23552
	global_load_lds_dwordx4 v[194:195], off
	s_mov_b32 m0, s16
	s_add_u32 s16, s30, 0x40000
	v_lshl_add_u64 v[228:229], s[30:31], 0, v[130:131]
	s_addc_u32 s17, s31, 0
	v_readfirstlane_b32 s6, v189
	global_load_lds_dwordx4 v[228:229], off
	v_lshl_add_u64 v[230:231], s[16:17], 0, v[32:33]
	s_mov_b32 m0, s6
	v_readfirstlane_b32 s6, v190
	global_load_lds_dwordx4 v[230:231], off
	v_lshl_add_u64 v[230:231], s[16:17], 0, v[130:131]
	s_mov_b32 m0, s6
	v_readfirstlane_b32 s6, v184
	global_load_lds_dwordx4 v[230:231], off
	v_lshl_add_u64 v[230:231], s[34:35], 0, v[32:33]
	s_mov_b32 m0, s6
	v_readfirstlane_b32 s6, v191
	global_load_lds_dwordx4 v[230:231], off
	v_lshl_add_u64 v[232:233], s[34:35], 0, v[130:131]
	s_mov_b32 m0, s6
	s_nop 0
	global_load_lds_dwordx4 v[232:233], off
	s_cmp_eq_u32 s101, 0
	s_cbranch_scc1 .Lskipw_recns_1
	s_waitcnt vmcnt(8)

; #define STAGE(bufoff, GB) do { const char* g_ = (GB); \
;         _Pragma("unroll") for (int i_ = 0; i_ < 2; ++i_) __builtin_amdgcn_global_load_lds((const unsigned*)(g_ + voff[i_]), (LAS3 unsigned*)(L + (bufoff) + stoff + i_ * 8192), 16, 0, 0); } while (0)
; #define LDA(dst, b, h) do { _Pragma("unroll") for (int m = 0; m < 4; ++m) _Pragma("unroll") for (int k = 0; k < 2; ++k) dst[m][k] = *(const LAS3 bf16x8*)(L + SA(b, h) + aoff + m * 2048 + k * 1024); } while (0)
; #define LDB(dst, b, h) do { _Pragma("unroll") for (int n = 0; n < 2; ++n) _Pragma("unroll") for (int k = 0; k < 2; ++k) dst[n][k] = *(const LAS3 bf16x8*)(L + SB(b, h) + boff + n * 2048 + k * 1024); } while (0)
; #define WAIT_V(n) asm volatile("s_waitcnt vmcnt(" #n ")" ::: "memory")
; #define WAIT_L(n) asm volatile("s_waitcnt lgkmcnt(" #n ")" ::: "memory")
; #define BAR __builtin_amdgcn_s_barrier()
; #define SCHED __builtin_amdgcn_sched_barrier(0)
; template <int EPI>
; DI void gemm_phase(const bf16_t* __restrict__ A, const bf16_t* __restrict__ Bt, const int K, const int N, const Params& p, const int layer_j, char* lds) {
;     ...
;         for (int t = 0; t < nt; t += 2) {
;             const bool last = (t == nt - 2);
;             const char* a1 = cA + (size_t)(t + 1) * kstep;
;             const char* a2 = last ? nA : cA + (size_t)(t + 2) * kstep; const char* b2 = last ? nB : cB + (size_t)(t + 2) * kstep;
;             const char* a3 = a2 + kstep; const char* b3 = b2 + kstep;
;             LDB(B0, 0, 0); LDB(B1, 0, 1); SCHED; LDA(At, 0, 0); STAGE(SA(1, 1), a1 + hstep);
;             WAIT_V(8); WAIT_L(0); BAR; MMA(0, 0, At, B0); MMA(0, 1, At, B1); BAR; SCHED;
;             LDA(At, 0, 1); STAGE(SB(0, 0), b2); STAGE(SB(0, 1), b2 + hstep); STAGE(SA(0, 0), a2);
;             WAIT_V(8); WAIT_L(0); BAR; MMA(1, 0, At, B0); MMA(1, 1, At, B1); BAR; SCHED;
.LBB0_374:
	s_cmp_eq_u32 s39, 1
	s_cselect_b32 s101, 1, s26
	v_add_u32_e32 v136, 0x10000, v140
	ds_read_b128 v[154:157], v136
	ds_read_b128 v[158:161], v136 offset:1024
	ds_read_b128 v[162:165], v136 offset:2048
	ds_read_b128 v[166:169], v136 offset:3072
	v_add_u32_e32 v136, 0x14000, v140
	s_add_u32 s28, s67, s26
	ds_read_b128 v[170:173], v136
	ds_read_b128 v[174:177], v136 offset:1024
	ds_read_b128 v[178:181], v136 offset:2048
	ds_read_b128 v[182:185], v136 offset:3072
	s_addc_u32 s29, s86, s27
	s_add_u32 s28, s28, 0x6681100
	s_addc_u32 s29, s29, 0
	s_add_u32 s88, s65, s26
	s_addc_u32 vcc_lo, s66, s27
	s_cmpk_eq_i32 s26, 0x700
	s_cselect_b32 s31, s15, s29
	s_cselect_b32 s30, s13, s28
	s_cselect_b32 s29, s64, vcc_lo
	s_cselect_b32 s28, s23, s88
	v_add_u32_e32 v190, 0xc000, v138
	v_lshl_add_u64 v[136:137], v[134:135], 0, s[26:27]
	v_readfirstlane_b32 s88, v190
	v_add_u32_e32 v190, 0xe000, v138
	s_mov_b32 m0, s88
	v_readfirstlane_b32 s88, v190
	ds_read_b128 v[186:189], v139
	ds_read_b128 v[204:207], v139 offset:1024
	ds_read_b128 v[208:211], v139 offset:2048
	ds_read_b128 v[212:215], v139 offset:3072
	ds_read_b128 v[216:219], v139 offset:4096
	ds_read_b128 v[220:223], v139 offset:5120
	ds_read_b128 v[224:227], v139 offset:6144
	ds_read_b128 v[228:231], v139 offset:7168
	global_load_lds_dwordx4 v[136:137], off
	v_lshl_add_u64 v[136:137], v[132:133], 0, s[26:27]
	s_mov_b32 m0, s88
	s_nop 0
	global_load_lds_dwordx4 v[136:137], off
	s_cmp_eq_u32 s101, 0
	s_cbranch_scc1 .Lskipw_att_0
	s_waitcnt vmcnt(8)
.Lskipw_att_0:
	s_waitcnt lgkmcnt(0)
	s_barrier
	s_setprio 1
	s_waitcnt lgkmcnt(0)
	v_mfma_f32_16x16x32_bf16 v[126:129], v[154:157], v[186:189], v[126:129]
	v_mfma_f32_16x16x32_bf16 v[110:113], v[162:165], v[186:189], v[110:113]
	v_mfma_f32_16x16x32_bf16 v[122:125], v[154:157], v[208:211], v[122:125]
	v_mfma_f32_16x16x32_bf16 v[106:109], v[162:165], v[208:211], v[106:109]
	v_mfma_f32_16x16x32_bf16 v[118:121], v[154:157], v[216:219], v[118:121]
	v_mfma_f32_16x16x32_bf16 v[102:105], v[162:165], v[216:219], v[102:105]
	v_mfma_f32_16x16x32_bf16 v[114:117], v[154:157], v[224:227], v[114:117]
	v_mfma_f32_16x16x32_bf16 v[94:97], v[162:165], v[224:227], v[94:97]
	v_mfma_f32_16x16x32_bf16 v[126:129], v[158:161], v[204:207], v[126:129]
	v_mfma_f32_16x16x32_bf16 v[110:113], v[166:169], v[204:207], v[110:113]
	v_mfma_f32_16x16x32_bf16 v[122:125], v[158:161], v[212:215], v[122:125]
	v_mfma_f32_16x16x32_bf16 v[106:109], v[166:169], v[212:215], v[106:109]
	v_mfma_f32_16x16x32_bf16 v[118:121], v[158:161], v[220:223], v[118:121]
	v_mfma_f32_16x16x32_bf16 v[102:105], v[166:169], v[220:223], v[102:105]
	v_mfma_f32_16x16x32_bf16 v[114:117], v[158:161], v[228:231], v[114:117]
	v_mfma_f32_16x16x32_bf16 v[94:97], v[166:169], v[228:231], v[94:97]
	s_setprio 0
	s_setprio 1
	v_mfma_f32_16x16x32_bf16 v[74:77], v[170:173], v[186:189], v[74:77]
	v_mfma_f32_16x16x32_bf16 v[34:37], v[178:181], v[186:189], v[34:37]
	v_mfma_f32_16x16x32_bf16 v[62:65], v[170:173], v[208:211], v[62:65]
	v_mfma_f32_16x16x32_bf16 v[24:27], v[178:181], v[208:211], v[24:27]
	v_mfma_f32_16x16x32_bf16 v[54:57], v[170:173], v[216:219], v[54:57]
	v_mfma_f32_16x16x32_bf16 v[20:23], v[178:181], v[216:219], v[20:23]
	v_mfma_f32_16x16x32_bf16 v[38:41], v[170:173], v[224:227], v[38:41]
	v_mfma_f32_16x16x32_bf16 v[12:15], v[178:181], v[224:227], v[12:15]
	v_mfma_f32_16x16x32_bf16 v[74:77], v[174:177], v[204:207], v[74:77]
	v_mfma_f32_16x16x32_bf16 v[34:37], v[182:185], v[204:207], v[34:37]
	v_mfma_f32_16x16x32_bf16 v[62:65], v[174:177], v[212:215], v[62:65]
	v_mfma_f32_16x16x32_bf16 v[24:27], v[182:185], v[212:215], v[24:27]
	v_mfma_f32_16x16x32_bf16 v[54:57], v[174:177], v[220:223], v[54:57]
	v_mfma_f32_16x16x32_bf16 v[20:23], v[182:185], v[220:223], v[20:23]
	v_mfma_f32_16x16x32_bf16 v[38:41], v[174:177], v[228:231], v[38:41]
	v_mfma_f32_16x16x32_bf16 v[12:15], v[182:185], v[228:231], v[12:15]
	s_setprio 0
	s_barrier
	v_readfirstlane_b32 s88, v141
	v_lshl_add_u64 v[136:137], s[28:29], 0, v[32:33]
	s_mov_b32 m0, s88
	v_readfirstlane_b32 s88, v142
	s_add_u32 vcc_lo, s28, 0x40000
	ds_read_b128 v[186:189], v139 offset:16384
	ds_read_b128 v[204:207], v139 offset:17408
	ds_read_b128 v[208:211], v139 offset:18432
	ds_read_b128 v[212:215], v139 offset:19456
	ds_read_b128 v[216:219], v139 offset:20480
	ds_read_b128 v[220:223], v139 offset:21504
	ds_read_b128 v[224:227], v139 offset:22528
	ds_read_b128 v[228:231], v139 offset:23552
	global_load_lds_dwordx4 v[136:137], off
	v_lshl_add_u64 v[190:191], s[28:29], 0, v[130:131]
	s_mov_b32 m0, s88
	s_addc_u32 vcc_hi, s29, 0
	v_readfirstlane_b32 s88, v143
	global_load_lds_dwordx4 v[190:191], off
	v_lshl_add_u64 v[194:195], vcc, 0, v[32:33]
	s_mov_b32 m0, s88
	v_readfirstlane_b32 s88, v144
	global_load_lds_dwordx4 v[194:195], off
	v_lshl_add_u64 v[194:195], vcc, 0, v[130:131]
	s_mov_b32 m0, s88
	v_readfirstlane_b32 s88, v138
	global_load_lds_dwordx4 v[194:195], off
	v_lshl_add_u64 v[194:195], s[30:31], 0, v[32:33]
	s_mov_b32 m0, s88
	v_readfirstlane_b32 s88, v145
	global_load_lds_dwordx4 v[194:195], off
	v_lshl_add_u64 v[232:233], s[30:31], 0, v[130:131]
	s_mov_b32 m0, s88
	s_nop 0
	global_load_lds_dwordx4 v[232:233], off
	s_cmp_eq_u32 s101, 0
	s_cbranch_scc1 .Lskipw_att_1
	s_waitcnt vmcnt(8)

; #define STAGE(bufoff, GB) do { const char* g_ = (GB); \
;         _Pragma("unroll") for (int i_ = 0; i_ < 2; ++i_) __builtin_amdgcn_global_load_lds((const unsigned*)(g_ + voff[i_]), (LAS3 unsigned*)(L + (bufoff) + stoff + i_ * 8192), 16, 0, 0); } while (0)
; #define LDA(dst, b, h) do { _Pragma("unroll") for (int m = 0; m < 4; ++m) _Pragma("unroll") for (int k = 0; k < 2; ++k) dst[m][k] = *(const LAS3 bf16x8*)(L + SA(b, h) + aoff + m * 2048 + k * 1024); } while (0)
; #define LDB(dst, b, h) do { _Pragma("unroll") for (int n = 0; n < 2; ++n) _Pragma("unroll") for (int k = 0; k < 2; ++k) dst[n][k] = *(const LAS3 bf16x8*)(L + SB(b, h) + boff + n * 2048 + k * 1024); } while (0)
; #define WAIT_V(n) asm volatile("s_waitcnt vmcnt(" #n ")" ::: "memory")
; #define WAIT_L(n) asm volatile("s_waitcnt lgkmcnt(" #n ")" ::: "memory")
; #define BAR __builtin_amdgcn_s_barrier()
; #define SCHED __builtin_amdgcn_sched_barrier(0)
; template <int EPI>
; DI void gemm_phase(const bf16_t* __restrict__ A, const bf16_t* __restrict__ Bt, const int K, const int N, const Params& p, const int layer_j, char* lds) {
;     ...
;             WAIT_V(8); WAIT_L(0); BAR; MMA(0, 0, At, B0); MMA(0, 1, At, B1); BAR; SCHED;
;             LDA(At, 0, 1); STAGE(SB(0, 0), b2); STAGE(SB(0, 1), b2 + hstep); STAGE(SA(0, 0), a2);
;             WAIT_V(8); WAIT_L(0); BAR; MMA(1, 0, At, B0); MMA(1, 1, At, B1); BAR; SCHED;
;             LDB(B0, 1, 0); LDB(B1, 1, 1); SCHED; LDA(At, 1, 0); STAGE(SA(0, 1), a2 + hstep);
;             WAIT_V(8); WAIT_L(0); BAR; MMA(0, 0, At, B0); MMA(0, 1, At, B1); BAR; SCHED;
;             LDA(At, 1, 1); STAGE(SB(1, 0), b3); STAGE(SB(1, 1), b3 + hstep); STAGE(SA(1, 0), a3);
.Lskipw_attns_0:
	s_waitcnt lgkmcnt(0)
	s_barrier
	s_setprio 1
	s_waitcnt lgkmcnt(0)
	v_mfma_f32_16x16x32_bf16 v[126:129], v[186:189], v[154:157], v[126:129]
	v_mfma_f32_16x16x32_bf16 v[110:113], v[186:189], v[162:165], v[110:113]
	v_mfma_f32_16x16x32_bf16 v[122:125], v[208:211], v[154:157], v[122:125]
	v_mfma_f32_16x16x32_bf16 v[106:109], v[208:211], v[162:165], v[106:109]
	v_mfma_f32_16x16x32_bf16 v[118:121], v[216:219], v[154:157], v[118:121]
	v_mfma_f32_16x16x32_bf16 v[102:105], v[216:219], v[162:165], v[102:105]
	v_mfma_f32_16x16x32_bf16 v[114:117], v[224:227], v[154:157], v[114:117]
	v_mfma_f32_16x16x32_bf16 v[94:97], v[224:227], v[162:165], v[94:97]
	v_mfma_f32_16x16x32_bf16 v[126:129], v[204:207], v[158:161], v[126:129]
	v_mfma_f32_16x16x32_bf16 v[110:113], v[204:207], v[166:169], v[110:113]
	v_mfma_f32_16x16x32_bf16 v[122:125], v[212:215], v[158:161], v[122:125]
	v_mfma_f32_16x16x32_bf16 v[106:109], v[212:215], v[166:169], v[106:109]
	v_mfma_f32_16x16x32_bf16 v[118:121], v[220:223], v[158:161], v[118:121]
	v_mfma_f32_16x16x32_bf16 v[102:105], v[220:223], v[166:169], v[102:105]
	v_mfma_f32_16x16x32_bf16 v[114:117], v[228:231], v[158:161], v[114:117]
	v_mfma_f32_16x16x32_bf16 v[94:97], v[228:231], v[166:169], v[94:97]
	s_setprio 0
	s_setprio 1
	v_mfma_f32_16x16x32_bf16 v[74:77], v[186:189], v[170:173], v[74:77]
	v_mfma_f32_16x16x32_bf16 v[34:37], v[186:189], v[178:181], v[34:37]
	v_mfma_f32_16x16x32_bf16 v[62:65], v[208:211], v[170:173], v[62:65]
	v_mfma_f32_16x16x32_bf16 v[24:27], v[208:211], v[178:181], v[24:27]
	v_mfma_f32_16x16x32_bf16 v[54:57], v[216:219], v[170:173], v[54:57]
	v_mfma_f32_16x16x32_bf16 v[20:23], v[216:219], v[178:181], v[20:23]
	v_mfma_f32_16x16x32_bf16 v[38:41], v[224:227], v[170:173], v[38:41]
	v_mfma_f32_16x16x32_bf16 v[12:15], v[224:227], v[178:181], v[12:15]
	v_mfma_f32_16x16x32_bf16 v[74:77], v[204:207], v[174:177], v[74:77]
	v_mfma_f32_16x16x32_bf16 v[34:37], v[204:207], v[182:185], v[34:37]
	v_mfma_f32_16x16x32_bf16 v[62:65], v[212:215], v[174:177], v[62:65]
	v_mfma_f32_16x16x32_bf16 v[24:27], v[212:215], v[182:185], v[24:27]
	v_mfma_f32_16x16x32_bf16 v[54:57], v[220:223], v[174:177], v[54:57]
	v_mfma_f32_16x16x32_bf16 v[20:23], v[220:223], v[182:185], v[20:23]
	v_mfma_f32_16x16x32_bf16 v[38:41], v[228:231], v[174:177], v[38:41]
	v_mfma_f32_16x16x32_bf16 v[12:15], v[228:231], v[182:185], v[12:15]
	s_setprio 0
	s_barrier
	v_readfirstlane_b32 s88, v141
	v_lshl_add_u64 v[136:137], s[28:29], 0, v[32:33]
	s_mov_b32 m0, s88
	v_readfirstlane_b32 s88, v142
	s_add_u32 vcc_lo, s28, 0x40000
	ds_read_b128 v[186:189], v139 offset:16384
	ds_read_b128 v[204:207], v139 offset:17408
	ds_read_b128 v[208:211], v139 offset:18432
	ds_read_b128 v[212:215], v139 offset:19456
	ds_read_b128 v[216:219], v139 offset:20480
	ds_read_b128 v[220:223], v139 offset:21504
	ds_read_b128 v[224:227], v139 offset:22528
	ds_read_b128 v[228:231], v139 offset:23552
	global_load_lds_dwordx4 v[136:137], off
	v_lshl_add_u64 v[190:191], s[28:29], 0, v[130:131]
	s_mov_b32 m0, s88
	s_addc_u32 vcc_hi, s29, 0
	v_readfirstlane_b32 s88, v143
	global_load_lds_dwordx4 v[190:191], off
	v_lshl_add_u64 v[194:195], vcc, 0, v[32:33]
	s_mov_b32 m0, s88
	v_readfirstlane_b32 s88, v144
	global_load_lds_dwordx4 v[194:195], off
	v_lshl_add_u64 v[194:195], vcc, 0, v[130:131]
	s_mov_b32 m0, s88
	v_readfirstlane_b32 s88, v138
	global_load_lds_dwordx4 v[194:195], off
	v_lshl_add_u64 v[194:195], s[30:31], 0, v[32:33]
	s_mov_b32 m0, s88
	v_readfirstlane_b32 s88, v145
	global_load_lds_dwordx4 v[194:195], off
	v_lshl_add_u64 v[232:233], s[30:31], 0, v[130:131]
	s_mov_b32 m0, s88
	s_nop 0
	global_load_lds_dwordx4 v[232:233], off
	s_cmp_eq_u32 s101, 0
	s_cbranch_scc1 .Lskipw_attns_1
	s_waitcnt vmcnt(8)
